# GLA scan: the two output MFMA16 chains interleaved, packed decay multiply
# baseline (speedup 1.0000x reference)
.Lsc_oloop:
.Lsc_obody0:
	ds_read_b128 v[128:131], v208 offset:0
	ds_read_b128 v[132:135], v208 offset:32
	ds_read_b128 v[136:139], v208 offset:64
	ds_read_b128 v[140:143], v208 offset:96
	ds_read_b128 v[96:99], v209 offset:0
	ds_read_b128 v[100:103], v209 offset:32
	ds_read_b128 v[104:107], v209 offset:64
	ds_read_b128 v[108:111], v209 offset:96
	ds_read_b128 v[112:115], v210 offset:0
	ds_read_b128 v[116:119], v210 offset:32
	ds_read_b128 v[120:123], v210 offset:64
	ds_read_b128 v[124:127], v210 offset:96
	v_cvt_pk_bf16_f32 v16, v0, v1
	v_cvt_pk_bf16_f32 v17, v2, v3
	v_cvt_pk_bf16_f32 v18, v4, v5
	v_cvt_pk_bf16_f32 v19, v6, v7
	v_cvt_pk_bf16_f32 v20, v8, v9
	v_cvt_pk_bf16_f32 v21, v10, v11
	v_cvt_pk_bf16_f32 v22, v12, v13
	v_cvt_pk_bf16_f32 v23, v14, v15
	s_waitcnt lgkmcnt(8)
	v_pk_mul_f32 v[0:1], v[0:1], v[128:129]
	v_pk_mul_f32 v[2:3], v[2:3], v[130:131]
	v_pk_mul_f32 v[4:5], v[4:5], v[132:133]
	v_pk_mul_f32 v[6:7], v[6:7], v[134:135]
	v_pk_mul_f32 v[8:9], v[8:9], v[136:137]
	v_pk_mul_f32 v[10:11], v[10:11], v[138:139]
	v_pk_mul_f32 v[12:13], v[12:13], v[140:141]
	v_pk_mul_f32 v[14:15], v[14:15], v[142:143]
	s_waitcnt lgkmcnt(0)
	s_nop 1
	v_mfma_f32_32x32x16_bf16 v[0:15], v[96:99], v[112:115], v[0:15]
	ds_read_b128 v[40:43], v89 offset:17408
	ds_read_b128 v[44:47], v89 offset:17472
	ds_read_b128 v[48:51], v89 offset:17536
	ds_read_b128 v[52:55], v89 offset:17600
	v_mfma_f32_32x32x16_bf16 v[0:15], v[100:103], v[116:119], v[0:15]
	ds_read_b128 v[128:131], v89 offset:18496
	ds_read_b128 v[132:135], v89 offset:18560
	ds_read_b128 v[136:139], v89 offset:18624
	ds_read_b128 v[140:143], v89 offset:18688
	v_mfma_f32_32x32x16_bf16 v[0:15], v[104:107], v[120:123], v[0:15]
	ds_write_b64 v164, v[16:17] offset:0
	ds_write_b64 v164, v[18:19] offset:16
	ds_write_b64 v164, v[20:21] offset:32
	ds_write_b64 v164, v[22:23] offset:48
	v_mfma_f32_32x32x16_bf16 v[0:15], v[108:111], v[124:127], v[0:15]
	s_waitcnt lgkmcnt(4)
	v_mfma_f32_16x16x32_bf16 v[24:27], v[40:43], v[72:75], 0
	v_mfma_f32_16x16x32_bf16 v[28:31], v[128:131], v[72:75], 0
	v_mfma_f32_16x16x32_bf16 v[24:27], v[44:47], v[76:79], v[24:27]
	v_mfma_f32_16x16x32_bf16 v[28:31], v[132:135], v[76:79], v[28:31]
	v_mfma_f32_16x16x32_bf16 v[24:27], v[48:51], v[80:83], v[24:27]
	v_mfma_f32_16x16x32_bf16 v[28:31], v[136:139], v[80:83], v[28:31]
	v_mfma_f32_16x16x32_bf16 v[24:27], v[52:55], v[84:87], v[24:27]
	v_mfma_f32_16x16x32_bf16 v[28:31], v[140:143], v[84:87], v[28:31]
	ds_read_b128 v[56:59], v88 offset:0
	ds_read_b128 v[60:63], v88 offset:64
	ds_read_b128 v[64:67], v88 offset:128
	ds_read_b128 v[68:71], v88 offset:192
	s_nop 7
	s_cmp_eq_u32 s44, 0
	s_cbranch_scc1 .Lsc_nost_ok0
	v_cvt_pk_bf16_f32 v24, v24, v25
	v_cvt_pk_bf16_f32 v25, v26, v27
	v_cvt_pk_bf16_f32 v26, v28, v29
	v_cvt_pk_bf16_f32 v27, v30, v31
	global_store_dwordx4 v90, v[24:27], s[42:43]
	s_add_u32 s42, s42, 0x68000
	s_addc_u32 s43, s43, 0

.Lsc_obody1:
	ds_read_b128 v[128:131], v208 offset:45568
	ds_read_b128 v[132:135], v208 offset:45600
	ds_read_b128 v[136:139], v208 offset:45632
	ds_read_b128 v[140:143], v208 offset:45664
	ds_read_b128 v[96:99], v209 offset:45568
	ds_read_b128 v[100:103], v209 offset:45600
	ds_read_b128 v[104:107], v209 offset:45632
	ds_read_b128 v[108:111], v209 offset:45664
	ds_read_b128 v[112:115], v210 offset:45568
	ds_read_b128 v[116:119], v210 offset:45600
	ds_read_b128 v[120:123], v210 offset:45632
	ds_read_b128 v[124:127], v210 offset:45664
	v_cvt_pk_bf16_f32 v16, v0, v1
	v_cvt_pk_bf16_f32 v17, v2, v3
	v_cvt_pk_bf16_f32 v18, v4, v5
	v_cvt_pk_bf16_f32 v19, v6, v7
	v_cvt_pk_bf16_f32 v20, v8, v9
	v_cvt_pk_bf16_f32 v21, v10, v11
	v_cvt_pk_bf16_f32 v22, v12, v13
	v_cvt_pk_bf16_f32 v23, v14, v15
	s_waitcnt lgkmcnt(8)
	v_pk_mul_f32 v[0:1], v[0:1], v[128:129]
	v_pk_mul_f32 v[2:3], v[2:3], v[130:131]
	v_pk_mul_f32 v[4:5], v[4:5], v[132:133]
	v_pk_mul_f32 v[6:7], v[6:7], v[134:135]
	v_pk_mul_f32 v[8:9], v[8:9], v[136:137]
	v_pk_mul_f32 v[10:11], v[10:11], v[138:139]
	v_pk_mul_f32 v[12:13], v[12:13], v[140:141]
	v_pk_mul_f32 v[14:15], v[14:15], v[142:143]
	s_waitcnt lgkmcnt(0)
	s_nop 1
	v_mfma_f32_32x32x16_bf16 v[0:15], v[96:99], v[112:115], v[0:15]
	ds_read_b128 v[40:43], v89 offset:0
	ds_read_b128 v[44:47], v89 offset:64
	ds_read_b128 v[48:51], v89 offset:128
	ds_read_b128 v[52:55], v89 offset:192
	v_mfma_f32_32x32x16_bf16 v[0:15], v[100:103], v[116:119], v[0:15]
	ds_read_b128 v[128:131], v89 offset:1088
	ds_read_b128 v[132:135], v89 offset:1152
	ds_read_b128 v[136:139], v89 offset:1216
	ds_read_b128 v[140:143], v89 offset:1280
	v_mfma_f32_32x32x16_bf16 v[0:15], v[104:107], v[120:123], v[0:15]
	ds_write_b64 v164, v[16:17] offset:17408
	ds_write_b64 v164, v[18:19] offset:17424
	ds_write_b64 v164, v[20:21] offset:17440
	ds_write_b64 v164, v[22:23] offset:17456
	v_mfma_f32_32x32x16_bf16 v[0:15], v[108:111], v[124:127], v[0:15]
	s_waitcnt lgkmcnt(4)
	v_mfma_f32_16x16x32_bf16 v[24:27], v[40:43], v[56:59], 0
	v_mfma_f32_16x16x32_bf16 v[28:31], v[128:131], v[56:59], 0
	v_mfma_f32_16x16x32_bf16 v[24:27], v[44:47], v[60:63], v[24:27]
	v_mfma_f32_16x16x32_bf16 v[28:31], v[132:135], v[60:63], v[28:31]
	v_mfma_f32_16x16x32_bf16 v[24:27], v[48:51], v[64:67], v[24:27]
	v_mfma_f32_16x16x32_bf16 v[28:31], v[136:139], v[64:67], v[28:31]
	v_mfma_f32_16x16x32_bf16 v[24:27], v[52:55], v[68:71], v[24:27]
	v_mfma_f32_16x16x32_bf16 v[28:31], v[140:143], v[68:71], v[28:31]
	ds_read_b128 v[72:75], v88 offset:45568
	ds_read_b128 v[76:79], v88 offset:45632
	ds_read_b128 v[80:83], v88 offset:45696
	ds_read_b128 v[84:87], v88 offset:45760
	s_nop 7
	v_cvt_pk_bf16_f32 v24, v24, v25
	v_cvt_pk_bf16_f32 v25, v26, v27
	v_cvt_pk_bf16_f32 v26, v28, v29
	v_cvt_pk_bf16_f32 v27, v30, v31
	global_store_dwordx4 v90, v[24:27], s[42:43]
	s_add_u32 s42, s42, 0x68000
	s_addc_u32 s43, s43, 0
	s_add_i32 s44, s44, 1
	s_waitcnt lgkmcnt(0)
	s_barrier
.Lsc_obody2:
	ds_read_b128 v[128:131], v208 offset:0
	ds_read_b128 v[132:135], v208 offset:32
	ds_read_b128 v[136:139], v208 offset:64
	ds_read_b128 v[140:143], v208 offset:96
	ds_read_b128 v[96:99], v209 offset:0
	ds_read_b128 v[100:103], v209 offset:32
	ds_read_b128 v[104:107], v209 offset:64
	ds_read_b128 v[108:111], v209 offset:96
	ds_read_b128 v[112:115], v210 offset:0
	ds_read_b128 v[116:119], v210 offset:32
	ds_read_b128 v[120:123], v210 offset:64
	ds_read_b128 v[124:127], v210 offset:96
	v_cvt_pk_bf16_f32 v16, v0, v1
	v_cvt_pk_bf16_f32 v17, v2, v3
	v_cvt_pk_bf16_f32 v18, v4, v5
	v_cvt_pk_bf16_f32 v19, v6, v7
	v_cvt_pk_bf16_f32 v20, v8, v9
	v_cvt_pk_bf16_f32 v21, v10, v11
	v_cvt_pk_bf16_f32 v22, v12, v13
	v_cvt_pk_bf16_f32 v23, v14, v15
	s_waitcnt lgkmcnt(8)
	v_pk_mul_f32 v[0:1], v[0:1], v[128:129]
	v_pk_mul_f32 v[2:3], v[2:3], v[130:131]
	v_pk_mul_f32 v[4:5], v[4:5], v[132:133]
	v_pk_mul_f32 v[6:7], v[6:7], v[134:135]
	v_pk_mul_f32 v[8:9], v[8:9], v[136:137]
	v_pk_mul_f32 v[10:11], v[10:11], v[138:139]
	v_pk_mul_f32 v[12:13], v[12:13], v[140:141]
	v_pk_mul_f32 v[14:15], v[14:15], v[142:143]
	s_waitcnt lgkmcnt(0)
	s_nop 1
	v_mfma_f32_32x32x16_bf16 v[0:15], v[96:99], v[112:115], v[0:15]
	ds_read_b128 v[40:43], v89 offset:17408
	ds_read_b128 v[44:47], v89 offset:17472
	ds_read_b128 v[48:51], v89 offset:17536
	ds_read_b128 v[52:55], v89 offset:17600
	v_mfma_f32_32x32x16_bf16 v[0:15], v[100:103], v[116:119], v[0:15]
	ds_read_b128 v[128:131], v89 offset:18496
	ds_read_b128 v[132:135], v89 offset:18560
	ds_read_b128 v[136:139], v89 offset:18624
	ds_read_b128 v[140:143], v89 offset:18688
	v_mfma_f32_32x32x16_bf16 v[0:15], v[104:107], v[120:123], v[0:15]
	ds_write_b64 v164, v[16:17] offset:0
	ds_write_b64 v164, v[18:19] offset:16
	ds_write_b64 v164, v[20:21] offset:32
	ds_write_b64 v164, v[22:23] offset:48
	v_mfma_f32_32x32x16_bf16 v[0:15], v[108:111], v[124:127], v[0:15]
	s_waitcnt lgkmcnt(4)
	v_mfma_f32_16x16x32_bf16 v[24:27], v[40:43], v[72:75], 0
	v_mfma_f32_16x16x32_bf16 v[28:31], v[128:131], v[72:75], 0
	v_mfma_f32_16x16x32_bf16 v[24:27], v[44:47], v[76:79], v[24:27]
	v_mfma_f32_16x16x32_bf16 v[28:31], v[132:135], v[76:79], v[28:31]
	v_mfma_f32_16x16x32_bf16 v[24:27], v[48:51], v[80:83], v[24:27]
	v_mfma_f32_16x16x32_bf16 v[28:31], v[136:139], v[80:83], v[28:31]
	v_mfma_f32_16x16x32_bf16 v[24:27], v[52:55], v[84:87], v[24:27]
	v_mfma_f32_16x16x32_bf16 v[28:31], v[140:143], v[84:87], v[28:31]
	ds_read_b128 v[56:59], v88 offset:0
	ds_read_b128 v[60:63], v88 offset:64
	ds_read_b128 v[64:67], v88 offset:128
	ds_read_b128 v[68:71], v88 offset:192
	s_nop 7
	v_cvt_pk_bf16_f32 v24, v24, v25
	v_cvt_pk_bf16_f32 v25, v26, v27
	v_cvt_pk_bf16_f32 v26, v28, v29
	v_cvt_pk_bf16_f32 v27, v30, v31
	global_store_dwordx4 v90, v[24:27], s[42:43]
	s_add_u32 s42, s42, 0x68000
	s_addc_u32 s43, s43, 0
	s_add_i32 s44, s44, 1
	s_waitcnt lgkmcnt(0)
	s_barrier
.Lsc_obody3:
	ds_read_b128 v[128:131], v208 offset:45568
	ds_read_b128 v[132:135], v208 offset:45600
	ds_read_b128 v[136:139], v208 offset:45632
	ds_read_b128 v[140:143], v208 offset:45664
	ds_read_b128 v[96:99], v209 offset:45568
	ds_read_b128 v[100:103], v209 offset:45600
	ds_read_b128 v[104:107], v209 offset:45632
	ds_read_b128 v[108:111], v209 offset:45664
	ds_read_b128 v[112:115], v210 offset:45568
	ds_read_b128 v[116:119], v210 offset:45600
	ds_read_b128 v[120:123], v210 offset:45632
	ds_read_b128 v[124:127], v210 offset:45664
	v_cvt_pk_bf16_f32 v16, v0, v1
	v_cvt_pk_bf16_f32 v17, v2, v3
	v_cvt_pk_bf16_f32 v18, v4, v5
	v_cvt_pk_bf16_f32 v19, v6, v7
	v_cvt_pk_bf16_f32 v20, v8, v9
	v_cvt_pk_bf16_f32 v21, v10, v11
	v_cvt_pk_bf16_f32 v22, v12, v13
	v_cvt_pk_bf16_f32 v23, v14, v15
	s_waitcnt lgkmcnt(8)
	v_pk_mul_f32 v[0:1], v[0:1], v[128:129]
	v_pk_mul_f32 v[2:3], v[2:3], v[130:131]
	v_pk_mul_f32 v[4:5], v[4:5], v[132:133]
	v_pk_mul_f32 v[6:7], v[6:7], v[134:135]
	v_pk_mul_f32 v[8:9], v[8:9], v[136:137]
	v_pk_mul_f32 v[10:11], v[10:11], v[138:139]
	v_pk_mul_f32 v[12:13], v[12:13], v[140:141]
	v_pk_mul_f32 v[14:15], v[14:15], v[142:143]
	s_waitcnt lgkmcnt(0)
	s_nop 1
	v_mfma_f32_32x32x16_bf16 v[0:15], v[96:99], v[112:115], v[0:15]
	ds_read_b128 v[40:43], v89 offset:0
	ds_read_b128 v[44:47], v89 offset:64
	ds_read_b128 v[48:51], v89 offset:128
	ds_read_b128 v[52:55], v89 offset:192
	v_mfma_f32_32x32x16_bf16 v[0:15], v[100:103], v[116:119], v[0:15]
	ds_read_b128 v[128:131], v89 offset:1088
	ds_read_b128 v[132:135], v89 offset:1152
	ds_read_b128 v[136:139], v89 offset:1216
	ds_read_b128 v[140:143], v89 offset:1280
	v_mfma_f32_32x32x16_bf16 v[0:15], v[104:107], v[120:123], v[0:15]
	ds_write_b64 v164, v[16:17] offset:17408
	ds_write_b64 v164, v[18:19] offset:17424
	ds_write_b64 v164, v[20:21] offset:17440
	ds_write_b64 v164, v[22:23] offset:17456
	v_mfma_f32_32x32x16_bf16 v[0:15], v[108:111], v[124:127], v[0:15]
	s_waitcnt lgkmcnt(4)
	v_mfma_f32_16x16x32_bf16 v[24:27], v[40:43], v[56:59], 0
	v_mfma_f32_16x16x32_bf16 v[28:31], v[128:131], v[56:59], 0
	v_mfma_f32_16x16x32_bf16 v[24:27], v[44:47], v[60:63], v[24:27]
	v_mfma_f32_16x16x32_bf16 v[28:31], v[132:135], v[60:63], v[28:31]
	v_mfma_f32_16x16x32_bf16 v[24:27], v[48:51], v[64:67], v[24:27]
	v_mfma_f32_16x16x32_bf16 v[28:31], v[136:139], v[64:67], v[28:31]
	v_mfma_f32_16x16x32_bf16 v[24:27], v[52:55], v[68:71], v[24:27]
	v_mfma_f32_16x16x32_bf16 v[28:31], v[140:143], v[68:71], v[28:31]
	ds_read_b128 v[72:75], v88 offset:45568
	ds_read_b128 v[76:79], v88 offset:45632
	ds_read_b128 v[80:83], v88 offset:45696
	ds_read_b128 v[84:87], v88 offset:45760
	s_nop 7
	v_cvt_pk_bf16_f32 v24, v24, v25
	v_cvt_pk_bf16_f32 v25, v26, v27
	v_cvt_pk_bf16_f32 v26, v28, v29
	v_cvt_pk_bf16_f32 v27, v30, v31
	global_store_dwordx4 v90, v[24:27], s[42:43]
	s_add_u32 s42, s42, 0x68000
	s_addc_u32 s43, s43, 0
	s_add_i32 s44, s44, 1
	s_waitcnt lgkmcnt(0)
	s_barrier
	s_cmp_eq_u32 s44, 64
	s_cbranch_scc1 .Lsc_oepi

.Lsc_obody5:
	ds_read_b128 v[128:131], v208 offset:45568
	ds_read_b128 v[132:135], v208 offset:45600
	ds_read_b128 v[136:139], v208 offset:45632
	ds_read_b128 v[140:143], v208 offset:45664
	ds_read_b128 v[96:99], v209 offset:45568
	ds_read_b128 v[100:103], v209 offset:45600
	ds_read_b128 v[104:107], v209 offset:45632
	ds_read_b128 v[108:111], v209 offset:45664
	ds_read_b128 v[112:115], v210 offset:45568
	ds_read_b128 v[116:119], v210 offset:45600
	ds_read_b128 v[120:123], v210 offset:45632
	ds_read_b128 v[124:127], v210 offset:45664
	v_cvt_pk_bf16_f32 v16, v0, v1
	v_cvt_pk_bf16_f32 v17, v2, v3
	v_cvt_pk_bf16_f32 v18, v4, v5
	v_cvt_pk_bf16_f32 v19, v6, v7
	v_cvt_pk_bf16_f32 v20, v8, v9
	v_cvt_pk_bf16_f32 v21, v10, v11
	v_cvt_pk_bf16_f32 v22, v12, v13
	v_cvt_pk_bf16_f32 v23, v14, v15
	s_waitcnt lgkmcnt(8)
	v_pk_mul_f32 v[0:1], v[0:1], v[128:129]
	v_pk_mul_f32 v[2:3], v[2:3], v[130:131]
	v_pk_mul_f32 v[4:5], v[4:5], v[132:133]
	v_pk_mul_f32 v[6:7], v[6:7], v[134:135]
	v_pk_mul_f32 v[8:9], v[8:9], v[136:137]
	v_pk_mul_f32 v[10:11], v[10:11], v[138:139]
	v_pk_mul_f32 v[12:13], v[12:13], v[140:141]
	v_pk_mul_f32 v[14:15], v[14:15], v[142:143]
	s_waitcnt lgkmcnt(0)
	s_nop 1
	v_mfma_f32_32x32x16_bf16 v[0:15], v[96:99], v[112:115], v[0:15]
	ds_read_b128 v[40:43], v89 offset:0
	ds_read_b128 v[44:47], v89 offset:64
	ds_read_b128 v[48:51], v89 offset:128
	ds_read_b128 v[52:55], v89 offset:192
	v_mfma_f32_32x32x16_bf16 v[0:15], v[100:103], v[116:119], v[0:15]
	ds_read_b128 v[128:131], v89 offset:1088
	ds_read_b128 v[132:135], v89 offset:1152
	ds_read_b128 v[136:139], v89 offset:1216
	ds_read_b128 v[140:143], v89 offset:1280
	v_mfma_f32_32x32x16_bf16 v[0:15], v[104:107], v[120:123], v[0:15]
	ds_write_b64 v164, v[16:17] offset:17408
	ds_write_b64 v164, v[18:19] offset:17424
	ds_write_b64 v164, v[20:21] offset:17440
	ds_write_b64 v164, v[22:23] offset:17456
	v_mfma_f32_32x32x16_bf16 v[0:15], v[108:111], v[124:127], v[0:15]
	s_waitcnt lgkmcnt(4)
	v_mfma_f32_16x16x32_bf16 v[24:27], v[40:43], v[56:59], 0
	v_mfma_f32_16x16x32_bf16 v[28:31], v[128:131], v[56:59], 0
	v_mfma_f32_16x16x32_bf16 v[24:27], v[44:47], v[60:63], v[24:27]
	v_mfma_f32_16x16x32_bf16 v[28:31], v[132:135], v[60:63], v[28:31]
	v_mfma_f32_16x16x32_bf16 v[24:27], v[48:51], v[64:67], v[24:27]
	v_mfma_f32_16x16x32_bf16 v[28:31], v[136:139], v[64:67], v[28:31]
	v_mfma_f32_16x16x32_bf16 v[24:27], v[52:55], v[68:71], v[24:27]
	v_mfma_f32_16x16x32_bf16 v[28:31], v[140:143], v[68:71], v[28:31]
	ds_read_b128 v[72:75], v88 offset:45568
	ds_read_b128 v[76:79], v88 offset:45632
	ds_read_b128 v[80:83], v88 offset:45696
	ds_read_b128 v[84:87], v88 offset:45760
	s_nop 7
	v_cvt_pk_bf16_f32 v24, v24, v25
	v_cvt_pk_bf16_f32 v25, v26, v27
	v_cvt_pk_bf16_f32 v26, v28, v29
	v_cvt_pk_bf16_f32 v27, v30, v31
	global_store_dwordx4 v90, v[24:27], s[42:43]
	s_add_u32 s42, s42, 0x68000
	s_addc_u32 s43, s43, 0
	s_add_i32 s44, s44, 1
	s_waitcnt lgkmcnt(0)
	s_barrier
	s_branch .Lsc_oloop
